# SEL tie-rank loop: software-pipelined LDS read (prefetch next pair)
# speedup vs baseline: 1.0041x; 1.0041x over previous
; DI void select_item(const P& p, int b, int quad4, int bid, char* smem, const SelPre& pre) {
;     ...
;       for (unsigned i = lane; i < c; i += 64) {
;         const unsigned ki = candk[i];
;         unsigned rank = 0;
;         for (unsigned j2 = 0; j2 < c; ++j2) { const unsigned kj = candk[j2]; rank += (kj > ki || (kj == ki && j2 < i)) ? 1u : 0u; }
;         if (rank < need && ngt + rank < 256u) dst[ngt + rank] = (unsigned short)candi[i];
;       }
.LBB0_495:
	v_lshl_add_u32 v11, v120, 2, v4
	s_waitcnt lgkmcnt(0)
	ds_read_b32 v2, v11 offset:5120
	s_mov_b64 s[4:5], -1
	v_mov_b32_e32 v3, 0
	v_mov_b32_e32 v5, 0
	s_and_saveexec_b64 s[28:29], vcc
	s_cbranch_execz .LBB0_499
	v_mov_b32_e32 v3, v120
	s_waitcnt lgkmcnt(0)
	v_mov_b32_e32 v5, v2
	s_mov_b32 s30, 1
	s_mov_b32 s31, 0
	s_mov_b64 s[62:63], 0
	v_mov_b32_e32 v12, 0
	v_mov_b32_e32 v13, 0
	v_mov_b32_e32 v14, v7
	v_mov_b32_e32 v15, v10
	ds_read_b64 v[16:17], v15
	v_add_u32_e32 v15, 8, v15
.LBB0_497:
	s_waitcnt lgkmcnt(0)
	v_mov_b32_e32 v160, v16
	v_mov_b32_e32 v161, v17
	ds_read_b64 v[16:17], v15
	v_cmp_lt_u32_e64 s[14:15], s31, v120
	v_cmp_lt_u32_e64 s[16:17], s30, v3
	v_add_u32_e32 v14, -2, v14
	s_add_i32 s31, s31, 2
	v_cmp_eq_u32_e64 s[10:11], v160, v2
	v_cmp_eq_u32_e64 s[12:13], v161, v5
	v_cmp_gt_u32_e64 s[4:5], v161, v5
	v_cmp_gt_u32_e64 s[8:9], v160, v2
	s_and_b64 s[12:13], s[16:17], s[12:13]
	s_and_b64 s[10:11], s[14:15], s[10:11]
	s_or_b64 s[8:9], s[8:9], s[10:11]
	s_or_b64 s[4:5], s[4:5], s[12:13]
	v_addc_co_u32_e64 v13, s[4:5], 0, v13, s[4:5]
	v_addc_co_u32_e64 v12, s[4:5], 0, v12, s[8:9]
	s_add_i32 s30, s30, 2
	v_cmp_eq_u32_e64 s[4:5], 0, v14
	v_add_u32_e32 v15, 8, v15
	s_or_b64 s[62:63], s[4:5], s[62:63]
	s_andn2_b64 exec, exec, s[62:63]
	s_cbranch_execnz .LBB0_497
	s_or_b64 exec, exec, s[62:63]
	s_waitcnt lgkmcnt(0)
	v_add_u32_e32 v3, v12, v13
	s_orn2_b64 s[4:5], s[0:1], exec
	v_mov_b32_e32 v5, v7
